# Res epilogue: second residual batch loads hoisted to epilogue top (one memory round trip)
# speedup vs baseline: 1.0009x; 1.0009x over previous
.LBB0_766:
	v_lshl_or_b32 v122, s71, 8, v189
	s_lshl_b32 s50, s36, 8
	v_add_u32_e32 v176, s50, v187
	v_ashrrev_i32_e32 v123, 31, v122
	v_lshlrev_b64 v[172:173], 1, v[122:123]
	v_ashrrev_i32_e32 v177, 31, v176
	v_lshl_add_u64 v[174:175], s[92:93], 0, v[172:173]
	v_lshlrev_b64 v[184:185], 11, v[176:177]
	v_lshl_add_u64 v[122:123], v[174:175], 0, v[184:185]
	global_load_dwordx4 v[192:195], v[122:123], off
	global_load_dwordx4 v[154:157], v[122:123], off offset:256
	v_or_b32_e32 v122, 16, v176
	v_ashrrev_i32_e32 v123, 31, v122
	v_lshlrev_b64 v[182:183], 11, v[122:123]
	v_lshl_add_u64 v[122:123], v[174:175], 0, v[182:183]
	global_load_dwordx4 v[150:153], v[122:123], off
	global_load_dwordx4 v[146:149], v[122:123], off offset:256
	v_or_b32_e32 v122, 32, v176
	v_ashrrev_i32_e32 v123, 31, v122
	v_lshlrev_b64 v[180:181], 11, v[122:123]
	v_lshl_add_u64 v[122:123], v[174:175], 0, v[180:181]
	global_load_dwordx4 v[142:145], v[122:123], off
	global_load_dwordx4 v[138:141], v[122:123], off offset:256
	v_or_b32_e32 v122, 48, v176
	v_ashrrev_i32_e32 v123, 31, v122
	v_lshlrev_b64 v[178:179], 11, v[122:123]
	v_lshl_add_u64 v[122:123], v[174:175], 0, v[178:179]
	v_lshl_add_u64 v[184:185], s[92:93], 0, v[184:185]
	global_load_dwordx4 v[134:137], v[122:123], off
	s_nop 0
	global_load_dwordx4 v[122:125], v[122:123], off offset:256
	v_add_u32_e32 v226, 0x80, v176
	v_ashrrev_i32_e32 v227, 31, v226
	v_lshlrev_b64 v[226:227], 11, v[226:227]
	v_lshl_add_u64 v[226:227], v[174:175], 0, v[226:227]
	global_load_dwordx4 v[198:201], v[226:227], off
	global_load_dwordx4 v[202:205], v[226:227], off offset:256
	v_add_u32_e32 v226, 0x90, v176
	v_ashrrev_i32_e32 v227, 31, v226
	v_lshlrev_b64 v[226:227], 11, v[226:227]
	v_lshl_add_u64 v[226:227], v[174:175], 0, v[226:227]
	global_load_dwordx4 v[206:209], v[226:227], off
	global_load_dwordx4 v[210:213], v[226:227], off offset:256
	v_add_u32_e32 v226, 0xa0, v176
	v_ashrrev_i32_e32 v227, 31, v226
	v_lshlrev_b64 v[226:227], 11, v[226:227]
	v_lshl_add_u64 v[226:227], v[174:175], 0, v[226:227]
	global_load_dwordx4 v[214:217], v[226:227], off
	global_load_dwordx4 v[218:221], v[226:227], off offset:256
	v_add_u32_e32 v226, 0xb0, v176
	v_ashrrev_i32_e32 v227, 31, v226
	v_lshlrev_b64 v[226:227], 11, v[226:227]
	v_lshl_add_u64 v[226:227], v[174:175], 0, v[226:227]
	global_load_dwordx4 v[222:225], v[226:227], off
	v_lshl_add_u64 v[184:185], v[184:185], 0, v[172:173]
	s_waitcnt vmcnt(7)
	v_lshlrev_b32_e32 v196, 16, v192
	v_and_b32_e32 v197, 0xffff0000, v192
	v_lshlrev_b32_e32 v192, 16, v193
	v_and_b32_e32 v193, 0xffff0000, v193
	v_pk_add_f32 v[132:133], v[132:133], v[192:193]
	v_lshlrev_b32_e32 v192, 16, v194
	v_and_b32_e32 v193, 0xffff0000, v194
	v_lshlrev_b32_e32 v194, 16, v195
	v_and_b32_e32 v195, 0xffff0000, v195
	v_pk_add_f32 v[130:131], v[130:131], v[196:197]
	v_pk_add_f32 v[194:195], v[128:129], v[194:195]
	v_pk_add_f32 v[128:129], v[126:127], v[192:193]
	v_cvt_pk_bf16_f32 v126, v130, v131
	v_cvt_pk_bf16_f32 v127, v132, v133
	s_nop 0
	v_cvt_pk_bf16_f32 v128, v128, v129
	v_cvt_pk_bf16_f32 v129, v194, v195
	global_store_dwordx4 v[184:185], v[126:129], off
	v_add_u32_e32 v226, 0xb0, v176
	v_ashrrev_i32_e32 v227, 31, v226
	v_lshlrev_b64 v[226:227], 11, v[226:227]
	v_lshl_add_u64 v[226:227], v[174:175], 0, v[226:227]
	global_load_dwordx4 v[192:195], v[226:227], off offset:256
	v_lshlrev_b32_e32 v130, 16, v126
	v_and_b32_e32 v131, 0xffff0000, v126
	v_lshlrev_b32_e32 v126, 16, v127
	v_and_b32_e32 v127, 0xffff0000, v127
	v_mul_f32_e32 v132, v127, v127
	v_pk_fma_f32 v[126:127], v[126:127], v[126:127], v[132:133] op_sel_hi:[1,1,0]
	v_lshlrev_b32_e32 v132, 16, v128
	v_lshlrev_b32_e32 v133, 16, v129
	v_and_b32_e32 v129, 0xffff0000, v129
	v_and_b32_e32 v128, 0xffff0000, v128
	v_pk_mul_f32 v[128:129], v[128:129], v[128:129]
	s_nop 0
	v_pk_fma_f32 v[128:129], v[132:133], v[132:133], v[128:129]
	v_lshlrev_b32_e32 v132, 16, v154
	v_and_b32_e32 v133, 0xffff0000, v154
	v_lshlrev_b32_e32 v154, 16, v155
	v_and_b32_e32 v155, 0xffff0000, v155
	v_pk_add_f32 v[120:121], v[120:121], v[154:155]
	v_pk_add_f32 v[118:119], v[118:119], v[132:133]
	v_lshlrev_b32_e32 v132, 16, v156
	v_and_b32_e32 v133, 0xffff0000, v156
	v_lshlrev_b32_e32 v154, 16, v157
	v_and_b32_e32 v155, 0xffff0000, v157
	v_pk_add_f32 v[154:155], v[116:117], v[154:155]
	v_pk_add_f32 v[116:117], v[114:115], v[132:133]
	v_cvt_pk_bf16_f32 v114, v118, v119
	v_cvt_pk_bf16_f32 v115, v120, v121
	s_nop 0
	v_cvt_pk_bf16_f32 v116, v116, v117
	v_cvt_pk_bf16_f32 v117, v154, v155
	global_store_dwordx4 v[184:185], v[114:117], off offset:256
	v_lshlrev_b32_e32 v121, 16, v116
	v_and_b32_e32 v119, 0xffff0000, v114
	v_and_b32_e32 v116, 0xffff0000, v116
	v_mul_f32_e32 v132, v116, v116
	v_lshlrev_b32_e32 v116, 16, v117
	v_mul_f32_e32 v133, v116, v116
	v_and_b32_e32 v116, 0xffff0000, v117
	v_mul_f32_e32 v154, v116, v116
	v_mul_f32_e32 v116, v131, v131
	v_pk_fma_f32 v[116:117], v[130:131], v[130:131], v[116:117] op_sel_hi:[1,1,0]
	v_mov_b32_e32 v130, v126
	v_mov_b32_e32 v120, v116
	v_mov_b32_e32 v131, v121
	v_pk_add_f32 v[116:117], v[116:117], v[126:127]
	v_pk_mul_f32 v[120:121], v[120:121], v[130:131]
	v_lshlrev_b32_e32 v118, 16, v114
	v_mov_b32_e32 v117, v121
	v_pk_add_f32 v[120:121], v[128:129], v[128:129] op_sel:[0,1] op_sel_hi:[1,0]
	v_lshlrev_b32_e32 v114, 16, v115
	v_mov_b32_e32 v121, v132
	v_and_b32_e32 v115, 0xffff0000, v115
	v_pk_add_f32 v[116:117], v[116:117], v[120:121]
	v_mul_f32_e32 v120, v119, v119
	v_pk_fma_f32 v[118:119], v[118:119], v[118:119], v[120:121] op_sel_hi:[1,1,0]
	v_mul_f32_e32 v120, v115, v115
	v_pk_fma_f32 v[114:115], v[114:115], v[114:115], v[120:121] op_sel_hi:[1,1,0]
	v_mov_b32_e32 v119, v133
	v_mov_b32_e32 v115, v154
	v_lshlrev_b32_e32 v120, 16, v150
	v_and_b32_e32 v121, 0xffff0000, v150
	v_lshlrev_b32_e32 v126, 16, v151
	v_and_b32_e32 v127, 0xffff0000, v151
	v_pk_add_f32 v[114:115], v[118:119], v[114:115]
	v_lshl_add_u64 v[118:119], s[92:93], 0, v[182:183]
	v_pk_add_f32 v[112:113], v[112:113], v[126:127]
	v_pk_add_f32 v[110:111], v[110:111], v[120:121]
	v_lshlrev_b32_e32 v120, 16, v152
	v_and_b32_e32 v121, 0xffff0000, v152
	v_lshlrev_b32_e32 v126, 16, v153
	v_and_b32_e32 v127, 0xffff0000, v153
	v_lshl_add_u64 v[118:119], v[118:119], 0, v[172:173]
	v_pk_add_f32 v[126:127], v[108:109], v[126:127]
	v_pk_add_f32 v[108:109], v[106:107], v[120:121]
	v_cvt_pk_bf16_f32 v106, v110, v111
	v_cvt_pk_bf16_f32 v107, v112, v113
	v_pk_add_f32 v[114:115], v[116:117], v[114:115]
	v_cvt_pk_bf16_f32 v108, v108, v109
	v_cvt_pk_bf16_f32 v109, v126, v127
	global_store_dwordx4 v[118:119], v[106:109], off
	v_lshlrev_b32_e32 v110, 16, v106
	v_and_b32_e32 v116, 64, v246
	v_and_b32_e32 v106, 0xffff0000, v106
	v_mul_f32_e32 v106, v106, v106
	v_fmac_f32_e32 v106, v110, v110
	v_lshlrev_b32_e32 v110, 16, v107
	v_and_b32_e32 v107, 0xffff0000, v107
	v_mul_f32_e32 v107, v107, v107
	v_fmac_f32_e32 v107, v110, v110
	v_add_f32_e32 v106, v106, v107
	v_lshlrev_b32_e32 v107, 16, v108
	v_and_b32_e32 v108, 0xffff0000, v108
	v_mul_f32_e32 v108, v108, v108
	v_fmac_f32_e32 v108, v107, v107
	v_lshlrev_b32_e32 v107, 16, v109
	v_and_b32_e32 v109, 0xffff0000, v109
	v_mul_f32_e32 v109, v109, v109
	v_fmac_f32_e32 v109, v107, v107
	v_add_f32_e32 v107, v108, v109
	v_add_f32_e32 v110, v106, v107
	v_lshlrev_b32_e32 v106, 16, v146
	v_and_b32_e32 v107, 0xffff0000, v146
	v_lshlrev_b32_e32 v108, 16, v147
	v_and_b32_e32 v109, 0xffff0000, v147
	v_pk_add_f32 v[104:105], v[104:105], v[108:109]
	v_pk_add_f32 v[102:103], v[102:103], v[106:107]
	v_lshlrev_b32_e32 v106, 16, v148
	v_and_b32_e32 v107, 0xffff0000, v148
	v_lshlrev_b32_e32 v108, 16, v149
	v_and_b32_e32 v109, 0xffff0000, v149
	v_pk_add_f32 v[108:109], v[100:101], v[108:109]
	v_pk_add_f32 v[100:101], v[98:99], v[106:107]
	v_cvt_pk_bf16_f32 v98, v102, v103
	v_cvt_pk_bf16_f32 v99, v104, v105
	v_and_b32_e32 v103, 0xffff0000, v142
	v_cvt_pk_bf16_f32 v100, v100, v101
	v_cvt_pk_bf16_f32 v101, v108, v109
	global_store_dwordx4 v[118:119], v[98:101], off offset:256
	v_lshlrev_b32_e32 v102, 16, v98
	v_lshlrev_b32_e32 v104, 16, v143
	v_and_b32_e32 v98, 0xffff0000, v98
	v_mul_f32_e32 v98, v98, v98
	v_fmac_f32_e32 v98, v102, v102
	v_lshlrev_b32_e32 v102, 16, v99
	v_and_b32_e32 v99, 0xffff0000, v99
	v_mul_f32_e32 v99, v99, v99
	v_fmac_f32_e32 v99, v102, v102
	v_add_f32_e32 v98, v98, v99
	v_lshlrev_b32_e32 v99, 16, v100
	v_and_b32_e32 v100, 0xffff0000, v100
	v_mul_f32_e32 v100, v100, v100
	v_fmac_f32_e32 v100, v99, v99
	v_lshlrev_b32_e32 v99, 16, v101
	v_and_b32_e32 v101, 0xffff0000, v101
	v_mul_f32_e32 v101, v101, v101
	v_fmac_f32_e32 v101, v99, v99
	v_lshlrev_b32_e32 v102, 16, v142
	v_and_b32_e32 v105, 0xffff0000, v143
	v_add_f32_e32 v99, v100, v101
	v_lshl_add_u64 v[100:101], s[92:93], 0, v[180:181]
	v_pk_add_f32 v[96:97], v[96:97], v[104:105]
	v_pk_add_f32 v[94:95], v[94:95], v[102:103]
	v_lshlrev_b32_e32 v102, 16, v144
	v_and_b32_e32 v103, 0xffff0000, v144
	v_lshlrev_b32_e32 v104, 16, v145
	v_and_b32_e32 v105, 0xffff0000, v145
	v_lshl_add_u64 v[100:101], v[100:101], 0, v[172:173]
	v_pk_add_f32 v[104:105], v[92:93], v[104:105]
	v_pk_add_f32 v[92:93], v[90:91], v[102:103]
	v_cvt_pk_bf16_f32 v90, v94, v95
	v_cvt_pk_bf16_f32 v91, v96, v97
	v_add_f32_e32 v114, v114, v115
	v_cvt_pk_bf16_f32 v92, v92, v93
	v_cvt_pk_bf16_f32 v93, v104, v105
	global_store_dwordx4 v[100:101], v[90:93], off
	v_lshlrev_b32_e32 v94, 16, v90
	v_xor_b32_e32 v115, 16, v246
	v_and_b32_e32 v90, 0xffff0000, v90
	v_mul_f32_e32 v90, v90, v90
	v_fmac_f32_e32 v90, v94, v94
	v_lshlrev_b32_e32 v94, 16, v91
	v_and_b32_e32 v91, 0xffff0000, v91
	v_mul_f32_e32 v91, v91, v91
	v_fmac_f32_e32 v91, v94, v94
	v_add_f32_e32 v90, v90, v91
	v_lshlrev_b32_e32 v91, 16, v92
	v_and_b32_e32 v92, 0xffff0000, v92
	v_mul_f32_e32 v92, v92, v92
	v_fmac_f32_e32 v92, v91, v91
	v_lshlrev_b32_e32 v91, 16, v93
	v_and_b32_e32 v93, 0xffff0000, v93
	v_mul_f32_e32 v93, v93, v93
	v_fmac_f32_e32 v93, v91, v91
	v_add_f32_e32 v91, v92, v93
	v_add_f32_e32 v94, v90, v91
	v_lshlrev_b32_e32 v90, 16, v138
	v_and_b32_e32 v91, 0xffff0000, v138
	v_lshlrev_b32_e32 v92, 16, v139
	v_and_b32_e32 v93, 0xffff0000, v139
	v_pk_add_f32 v[88:89], v[88:89], v[92:93]
	v_pk_add_f32 v[86:87], v[86:87], v[90:91]
	v_lshlrev_b32_e32 v90, 16, v140
	v_and_b32_e32 v91, 0xffff0000, v140
	v_lshlrev_b32_e32 v92, 16, v141
	v_and_b32_e32 v93, 0xffff0000, v141
	v_pk_add_f32 v[92:93], v[84:85], v[92:93]
	v_pk_add_f32 v[84:85], v[82:83], v[90:91]
	v_cvt_pk_bf16_f32 v82, v86, v87
	v_cvt_pk_bf16_f32 v83, v88, v89
	v_add_u32_e32 v116, 64, v116
	v_cvt_pk_bf16_f32 v84, v84, v85
	v_cvt_pk_bf16_f32 v85, v92, v93
	global_store_dwordx4 v[100:101], v[82:85], off offset:256
	v_lshlrev_b32_e32 v86, 16, v82
	v_cmp_lt_i32_e32 vcc, v115, v116
	v_and_b32_e32 v82, 0xffff0000, v82
	v_mul_f32_e32 v82, v82, v82
	v_fmac_f32_e32 v82, v86, v86
	v_lshlrev_b32_e32 v86, 16, v83
	v_and_b32_e32 v83, 0xffff0000, v83
	v_mul_f32_e32 v83, v83, v83
	v_fmac_f32_e32 v83, v86, v86
	v_add_f32_e32 v82, v82, v83
	v_lshlrev_b32_e32 v83, 16, v84
	v_and_b32_e32 v84, 0xffff0000, v84
	v_mul_f32_e32 v84, v84, v84
	v_fmac_f32_e32 v84, v83, v83
	v_lshlrev_b32_e32 v83, 16, v85
	v_and_b32_e32 v85, 0xffff0000, v85
	v_mul_f32_e32 v85, v85, v85
	v_fmac_f32_e32 v85, v83, v83
	v_cndmask_b32_e32 v115, v246, v115, vcc
	v_add_f32_e32 v82, v94, v82
	v_add_f32_e32 v83, v84, v85
	v_lshlrev_b32_e32 v117, 2, v115
	v_add_f32_e32 v82, v82, v83
	ds_bpermute_b32 v83, v117, v82
	v_lshlrev_b32_e32 v84, 16, v134
	v_and_b32_e32 v85, 0xffff0000, v134
	v_lshlrev_b32_e32 v86, 16, v135
	v_and_b32_e32 v87, 0xffff0000, v135
	s_waitcnt lgkmcnt(0)
	v_add_f32_e32 v96, v82, v83
	v_lshl_add_u64 v[82:83], s[92:93], 0, v[178:179]
	v_pk_add_f32 v[80:81], v[80:81], v[86:87]
	v_pk_add_f32 v[78:79], v[78:79], v[84:85]
	v_lshlrev_b32_e32 v84, 16, v136
	v_and_b32_e32 v85, 0xffff0000, v136
	v_lshlrev_b32_e32 v86, 16, v137
	v_and_b32_e32 v87, 0xffff0000, v137
	v_lshl_add_u64 v[82:83], v[82:83], 0, v[172:173]
	v_pk_add_f32 v[86:87], v[76:77], v[86:87]
	v_pk_add_f32 v[76:77], v[74:75], v[84:85]
	v_cvt_pk_bf16_f32 v74, v78, v79
	v_cvt_pk_bf16_f32 v75, v80, v81
	v_add_f32_e32 v98, v110, v98
	v_cvt_pk_bf16_f32 v76, v76, v77
	v_cvt_pk_bf16_f32 v77, v86, v87
	global_store_dwordx4 v[82:83], v[74:77], off
	v_lshlrev_b32_e32 v78, 16, v74
	ds_bpermute_b32 v115, v117, v114
	v_and_b32_e32 v74, 0xffff0000, v74
	v_mul_f32_e32 v74, v74, v74
	v_fmac_f32_e32 v74, v78, v78
	v_lshlrev_b32_e32 v78, 16, v75
	v_and_b32_e32 v75, 0xffff0000, v75
	v_mul_f32_e32 v75, v75, v75
	v_fmac_f32_e32 v75, v78, v78
	v_add_f32_e32 v74, v74, v75
	v_lshlrev_b32_e32 v75, 16, v76
	v_and_b32_e32 v76, 0xffff0000, v76
	v_mul_f32_e32 v76, v76, v76
	v_fmac_f32_e32 v76, v75, v75
	v_lshlrev_b32_e32 v75, 16, v77
	v_and_b32_e32 v77, 0xffff0000, v77
	v_mul_f32_e32 v77, v77, v77
	v_fmac_f32_e32 v77, v75, v75
	v_add_f32_e32 v75, v76, v77
	v_add_f32_e32 v78, v74, v75
	v_lshlrev_b32_e32 v74, 16, v122
	v_and_b32_e32 v75, 0xffff0000, v122
	v_lshlrev_b32_e32 v76, 16, v123
	v_and_b32_e32 v77, 0xffff0000, v123
	v_pk_add_f32 v[72:73], v[72:73], v[76:77]
	v_pk_add_f32 v[70:71], v[70:71], v[74:75]
	v_lshlrev_b32_e32 v74, 16, v124
	v_and_b32_e32 v75, 0xffff0000, v124
	v_lshlrev_b32_e32 v76, 16, v125
	v_and_b32_e32 v77, 0xffff0000, v125
	v_pk_add_f32 v[76:77], v[68:69], v[76:77]
	v_pk_add_f32 v[68:69], v[66:67], v[74:75]
	v_cvt_pk_bf16_f32 v66, v70, v71
	v_cvt_pk_bf16_f32 v67, v72, v73
	v_add_f32_e32 v98, v98, v99
	v_cvt_pk_bf16_f32 v68, v68, v69
	v_cvt_pk_bf16_f32 v69, v76, v77
	global_store_dwordx4 v[82:83], v[66:69], off offset:256
	v_lshlrev_b32_e32 v70, 16, v66
	ds_bpermute_b32 v99, v117, v98
	v_and_b32_e32 v66, 0xffff0000, v66
	v_mul_f32_e32 v66, v66, v66
	v_fmac_f32_e32 v66, v70, v70
	v_lshlrev_b32_e32 v70, 16, v67
	v_and_b32_e32 v67, 0xffff0000, v67
	v_mul_f32_e32 v67, v67, v67
	v_fmac_f32_e32 v67, v70, v70
	v_add_f32_e32 v66, v66, v67
	v_lshlrev_b32_e32 v67, 16, v68
	v_and_b32_e32 v68, 0xffff0000, v68
	v_mul_f32_e32 v68, v68, v68
	v_fmac_f32_e32 v68, v67, v67
	v_lshlrev_b32_e32 v67, 16, v69
	v_and_b32_e32 v69, 0xffff0000, v69
	v_mul_f32_e32 v69, v69, v69
	v_fmac_f32_e32 v69, v67, v67
	v_add_f32_e32 v66, v78, v66
	v_add_f32_e32 v67, v68, v69
	v_add_f32_e32 v66, v66, v67
	ds_bpermute_b32 v67, v117, v66
	s_waitcnt lgkmcnt(2)
	v_add_f32_e32 v114, v114, v115
	v_xor_b32_e32 v115, 32, v246
	v_cmp_lt_i32_e32 vcc, v115, v116
	s_waitcnt lgkmcnt(1)
	v_add_f32_e32 v98, v98, v99
	s_waitcnt lgkmcnt(0)
	v_add_f32_e32 v100, v66, v67
	v_add_u32_e32 v226, 0x80, v176
	v_ashrrev_i32_e32 v227, 31, v226
	v_lshlrev_b64 v[94:95], 11, v[226:227]
	v_add_u32_e32 v226, 0x90, v176
	v_ashrrev_i32_e32 v227, 31, v226
	v_lshlrev_b64 v[110:111], 11, v[226:227]
	v_add_u32_e32 v226, 0xa0, v176
	v_ashrrev_i32_e32 v227, 31, v226
	v_lshlrev_b64 v[92:93], 11, v[226:227]
	v_add_u32_e32 v226, 0xb0, v176
	v_ashrrev_i32_e32 v227, 31, v226
	v_lshlrev_b64 v[90:91], 11, v[226:227]
	s_waitcnt vmcnt(7)
	v_lshl_add_u64 v[94:95], s[92:93], 0, v[94:95]
	v_lshl_add_u64 v[94:95], v[94:95], 0, v[172:173]
	v_cndmask_b32_e32 v115, v246, v115, vcc
	v_lshlrev_b32_e32 v116, 2, v115
	ds_bpermute_b32 v115, v116, v114
	ds_bpermute_b32 v99, v116, v98
	ds_bpermute_b32 v97, v116, v96
	ds_bpermute_b32 v101, v116, v100
	v_cmp_lt_i32_e32 vcc, 1, v186
	v_lshlrev_b32_e32 v112, 16, v198
	v_and_b32_e32 v113, 0xffff0000, v198
	v_lshlrev_b32_e32 v198, 16, v199
	v_and_b32_e32 v199, 0xffff0000, v199
	v_pk_add_f32 v[64:65], v[64:65], v[198:199]
	v_lshlrev_b32_e32 v198, 16, v200
	v_and_b32_e32 v199, 0xffff0000, v200
	v_lshlrev_b32_e32 v200, 16, v201
	v_and_b32_e32 v201, 0xffff0000, v201
	v_pk_add_f32 v[62:63], v[62:63], v[112:113]
	v_pk_add_f32 v[200:201], v[60:61], v[200:201]
	v_pk_add_f32 v[60:61], v[58:59], v[198:199]
	v_cvt_pk_bf16_f32 v58, v62, v63
	v_cvt_pk_bf16_f32 v59, v64, v65
	s_nop 0
	v_cvt_pk_bf16_f32 v60, v60, v61
	v_cvt_pk_bf16_f32 v61, v200, v201
	global_store_dwordx4 v[94:95], v[58:61], off
	v_lshlrev_b32_e32 v62, 16, v58
	s_nop 0
	v_and_b32_e32 v58, 0xffff0000, v58
	v_mul_f32_e32 v58, v58, v58
	v_fmac_f32_e32 v58, v62, v62
	v_lshlrev_b32_e32 v62, 16, v59
	v_and_b32_e32 v59, 0xffff0000, v59
	v_mul_f32_e32 v59, v59, v59
	v_fmac_f32_e32 v59, v62, v62
	v_add_f32_e32 v58, v58, v59
	v_lshlrev_b32_e32 v59, 16, v60
	v_and_b32_e32 v60, 0xffff0000, v60
	v_mul_f32_e32 v60, v60, v60
	v_fmac_f32_e32 v60, v59, v59
	v_lshlrev_b32_e32 v59, 16, v61
	v_and_b32_e32 v61, 0xffff0000, v61
	v_mul_f32_e32 v61, v61, v61
	v_fmac_f32_e32 v61, v59, v59
	v_add_f32_e32 v59, v60, v61
	v_add_f32_e32 v62, v58, v59
	v_lshlrev_b32_e32 v58, 16, v202
	v_and_b32_e32 v59, 0xffff0000, v202
	v_lshlrev_b32_e32 v60, 16, v203
	v_and_b32_e32 v61, 0xffff0000, v203
	v_pk_add_f32 v[56:57], v[56:57], v[60:61]
	v_pk_add_f32 v[54:55], v[54:55], v[58:59]
	v_lshlrev_b32_e32 v58, 16, v204
	v_and_b32_e32 v59, 0xffff0000, v204
	v_lshlrev_b32_e32 v60, 16, v205
	v_and_b32_e32 v61, 0xffff0000, v205
	v_pk_add_f32 v[60:61], v[52:53], v[60:61]
	v_pk_add_f32 v[52:53], v[50:51], v[58:59]
	v_cvt_pk_bf16_f32 v50, v54, v55
	v_cvt_pk_bf16_f32 v51, v56, v57
	v_and_b32_e32 v55, 0xffff0000, v206
	v_cvt_pk_bf16_f32 v52, v52, v53
	v_cvt_pk_bf16_f32 v53, v60, v61
	global_store_dwordx4 v[94:95], v[50:53], off offset:256
	v_lshlrev_b32_e32 v54, 16, v50
	v_lshlrev_b32_e32 v56, 16, v207
	v_and_b32_e32 v50, 0xffff0000, v50
	v_mul_f32_e32 v50, v50, v50
	v_fmac_f32_e32 v50, v54, v54
	v_lshlrev_b32_e32 v54, 16, v51
	v_and_b32_e32 v51, 0xffff0000, v51
	v_mul_f32_e32 v51, v51, v51
	v_fmac_f32_e32 v51, v54, v54
	v_add_f32_e32 v50, v50, v51
	v_lshlrev_b32_e32 v51, 16, v52
	v_and_b32_e32 v52, 0xffff0000, v52
	v_mul_f32_e32 v52, v52, v52
	v_fmac_f32_e32 v52, v51, v51
	v_lshlrev_b32_e32 v51, 16, v53
	v_and_b32_e32 v53, 0xffff0000, v53
	v_mul_f32_e32 v53, v53, v53
	v_fmac_f32_e32 v53, v51, v51
	v_lshlrev_b32_e32 v54, 16, v206
	v_and_b32_e32 v57, 0xffff0000, v207
	v_add_f32_e32 v51, v52, v53
	v_lshl_add_u64 v[52:53], s[92:93], 0, v[110:111]
	v_pk_add_f32 v[48:49], v[48:49], v[56:57]
	v_pk_add_f32 v[46:47], v[46:47], v[54:55]
	v_lshlrev_b32_e32 v54, 16, v208
	v_and_b32_e32 v55, 0xffff0000, v208
	v_lshlrev_b32_e32 v56, 16, v209
	v_and_b32_e32 v57, 0xffff0000, v209
	v_lshl_add_u64 v[52:53], v[52:53], 0, v[172:173]
	v_pk_add_f32 v[56:57], v[44:45], v[56:57]
	v_pk_add_f32 v[44:45], v[42:43], v[54:55]
	v_cvt_pk_bf16_f32 v42, v46, v47
	v_cvt_pk_bf16_f32 v43, v48, v49
	v_add_f32_e32 v50, v62, v50
	v_cvt_pk_bf16_f32 v44, v44, v45
	v_cvt_pk_bf16_f32 v45, v56, v57
	global_store_dwordx4 v[52:53], v[42:45], off
	v_lshlrev_b32_e32 v46, 16, v42
	v_add_f32_e32 v50, v50, v51
	v_and_b32_e32 v42, 0xffff0000, v42
	v_mul_f32_e32 v42, v42, v42
	v_fmac_f32_e32 v42, v46, v46
	v_lshlrev_b32_e32 v46, 16, v43
	v_and_b32_e32 v43, 0xffff0000, v43
	v_mul_f32_e32 v43, v43, v43
	v_fmac_f32_e32 v43, v46, v46
	v_add_f32_e32 v42, v42, v43
	v_lshlrev_b32_e32 v43, 16, v44
	v_and_b32_e32 v44, 0xffff0000, v44
	v_mul_f32_e32 v44, v44, v44
	v_fmac_f32_e32 v44, v43, v43
	v_lshlrev_b32_e32 v43, 16, v45
	v_and_b32_e32 v45, 0xffff0000, v45
	v_mul_f32_e32 v45, v45, v45
	v_fmac_f32_e32 v45, v43, v43
	v_add_f32_e32 v43, v44, v45
	v_add_f32_e32 v46, v42, v43
	v_lshlrev_b32_e32 v42, 16, v210
	v_and_b32_e32 v43, 0xffff0000, v210
	v_lshlrev_b32_e32 v44, 16, v211
	v_and_b32_e32 v45, 0xffff0000, v211
	v_pk_add_f32 v[40:41], v[40:41], v[44:45]
	v_pk_add_f32 v[38:39], v[38:39], v[42:43]
	v_lshlrev_b32_e32 v42, 16, v212
	v_and_b32_e32 v43, 0xffff0000, v212
	v_lshlrev_b32_e32 v44, 16, v213
	v_and_b32_e32 v45, 0xffff0000, v213
	v_pk_add_f32 v[44:45], v[36:37], v[44:45]
	v_pk_add_f32 v[36:37], v[34:35], v[42:43]
	v_cvt_pk_bf16_f32 v34, v38, v39
	v_cvt_pk_bf16_f32 v35, v40, v41
	v_and_b32_e32 v39, 0xffff0000, v214
	v_cvt_pk_bf16_f32 v36, v36, v37
	v_cvt_pk_bf16_f32 v37, v44, v45
	global_store_dwordx4 v[52:53], v[34:37], off offset:256
	v_lshlrev_b32_e32 v38, 16, v34
	v_lshlrev_b32_e32 v40, 16, v215
	v_and_b32_e32 v34, 0xffff0000, v34
	v_mul_f32_e32 v34, v34, v34
	v_fmac_f32_e32 v34, v38, v38
	v_lshlrev_b32_e32 v38, 16, v35
	v_and_b32_e32 v35, 0xffff0000, v35
	v_mul_f32_e32 v35, v35, v35
	v_fmac_f32_e32 v35, v38, v38
	v_add_f32_e32 v34, v34, v35
	v_lshlrev_b32_e32 v35, 16, v36
	v_and_b32_e32 v36, 0xffff0000, v36
	v_mul_f32_e32 v36, v36, v36
	v_fmac_f32_e32 v36, v35, v35
	v_lshlrev_b32_e32 v35, 16, v37
	v_and_b32_e32 v37, 0xffff0000, v37
	v_mul_f32_e32 v37, v37, v37
	v_fmac_f32_e32 v37, v35, v35
	v_lshlrev_b32_e32 v38, 16, v214
	v_and_b32_e32 v41, 0xffff0000, v215
	v_add_f32_e32 v35, v36, v37
	v_lshl_add_u64 v[36:37], s[92:93], 0, v[92:93]
	v_pk_add_f32 v[32:33], v[32:33], v[40:41]
	v_pk_add_f32 v[30:31], v[30:31], v[38:39]
	v_lshlrev_b32_e32 v38, 16, v216
	v_and_b32_e32 v39, 0xffff0000, v216
	v_lshlrev_b32_e32 v40, 16, v217
	v_and_b32_e32 v41, 0xffff0000, v217
	v_lshl_add_u64 v[36:37], v[36:37], 0, v[172:173]
	v_pk_add_f32 v[40:41], v[28:29], v[40:41]
	v_pk_add_f32 v[28:29], v[26:27], v[38:39]
	v_cvt_pk_bf16_f32 v26, v30, v31
	v_cvt_pk_bf16_f32 v27, v32, v33
	v_add_f32_e32 v34, v46, v34
	v_cvt_pk_bf16_f32 v28, v28, v29
	v_cvt_pk_bf16_f32 v29, v40, v41
	global_store_dwordx4 v[36:37], v[26:29], off
	v_lshlrev_b32_e32 v30, 16, v26
	v_add_f32_e32 v34, v34, v35
	v_and_b32_e32 v26, 0xffff0000, v26
	v_mul_f32_e32 v26, v26, v26
	v_fmac_f32_e32 v26, v30, v30
	v_lshlrev_b32_e32 v30, 16, v27
	v_and_b32_e32 v27, 0xffff0000, v27
	v_mul_f32_e32 v27, v27, v27
	v_fmac_f32_e32 v27, v30, v30
	v_add_f32_e32 v26, v26, v27
	v_lshlrev_b32_e32 v27, 16, v28
	v_and_b32_e32 v28, 0xffff0000, v28
	v_mul_f32_e32 v28, v28, v28
	v_fmac_f32_e32 v28, v27, v27
	v_lshlrev_b32_e32 v27, 16, v29
	v_and_b32_e32 v29, 0xffff0000, v29
	v_mul_f32_e32 v29, v29, v29
	v_fmac_f32_e32 v29, v27, v27
	v_add_f32_e32 v27, v28, v29
	v_add_f32_e32 v30, v26, v27
	v_lshlrev_b32_e32 v26, 16, v218
	v_and_b32_e32 v27, 0xffff0000, v218
	v_lshlrev_b32_e32 v28, 16, v219
	v_and_b32_e32 v29, 0xffff0000, v219
	v_pk_add_f32 v[24:25], v[24:25], v[28:29]
	v_pk_add_f32 v[22:23], v[22:23], v[26:27]
	v_lshlrev_b32_e32 v26, 16, v220
	v_and_b32_e32 v27, 0xffff0000, v220
	v_lshlrev_b32_e32 v28, 16, v221
	v_and_b32_e32 v29, 0xffff0000, v221
	v_pk_add_f32 v[28:29], v[20:21], v[28:29]
	v_pk_add_f32 v[20:21], v[18:19], v[26:27]
	v_cvt_pk_bf16_f32 v18, v22, v23
	v_cvt_pk_bf16_f32 v19, v24, v25
	v_and_b32_e32 v23, 0xffff0000, v222
	v_cvt_pk_bf16_f32 v20, v20, v21
	v_cvt_pk_bf16_f32 v21, v28, v29
	global_store_dwordx4 v[36:37], v[18:21], off offset:256
	v_lshlrev_b32_e32 v22, 16, v18
	v_lshlrev_b32_e32 v24, 16, v223
	v_and_b32_e32 v18, 0xffff0000, v18
	v_mul_f32_e32 v18, v18, v18
	v_fmac_f32_e32 v18, v22, v22
	v_lshlrev_b32_e32 v22, 16, v19
	v_and_b32_e32 v19, 0xffff0000, v19
	v_mul_f32_e32 v19, v19, v19
	v_fmac_f32_e32 v19, v22, v22
	v_add_f32_e32 v18, v18, v19
	v_lshlrev_b32_e32 v19, 16, v20
	v_and_b32_e32 v20, 0xffff0000, v20
	v_mul_f32_e32 v20, v20, v20
	v_fmac_f32_e32 v20, v19, v19
	v_lshlrev_b32_e32 v19, 16, v21
	v_and_b32_e32 v21, 0xffff0000, v21
	v_mul_f32_e32 v21, v21, v21
	v_fmac_f32_e32 v21, v19, v19
	v_lshlrev_b32_e32 v22, 16, v222
	v_and_b32_e32 v25, 0xffff0000, v223
	v_add_f32_e32 v19, v20, v21
	v_lshl_add_u64 v[20:21], s[92:93], 0, v[90:91]
	v_pk_add_f32 v[16:17], v[16:17], v[24:25]
	v_pk_add_f32 v[14:15], v[14:15], v[22:23]
	v_lshlrev_b32_e32 v22, 16, v224
	v_and_b32_e32 v23, 0xffff0000, v224
	v_lshlrev_b32_e32 v24, 16, v225
	v_and_b32_e32 v25, 0xffff0000, v225
	v_lshl_add_u64 v[20:21], v[20:21], 0, v[172:173]
	v_pk_add_f32 v[24:25], v[12:13], v[24:25]
	v_pk_add_f32 v[12:13], v[10:11], v[22:23]
	v_cvt_pk_bf16_f32 v10, v14, v15
	v_cvt_pk_bf16_f32 v11, v16, v17
	v_add_f32_e32 v18, v30, v18
	v_cvt_pk_bf16_f32 v12, v12, v13
	v_cvt_pk_bf16_f32 v13, v24, v25
	global_store_dwordx4 v[20:21], v[10:13], off
	v_lshlrev_b32_e32 v14, 16, v10
	v_add_f32_e32 v18, v18, v19
	v_and_b32_e32 v10, 0xffff0000, v10
	v_mul_f32_e32 v10, v10, v10
	v_fmac_f32_e32 v10, v14, v14
	v_lshlrev_b32_e32 v14, 16, v11
	v_and_b32_e32 v11, 0xffff0000, v11
	v_mul_f32_e32 v11, v11, v11
	v_fmac_f32_e32 v11, v14, v14
	v_add_f32_e32 v10, v10, v11
	v_lshlrev_b32_e32 v11, 16, v12
	v_and_b32_e32 v12, 0xffff0000, v12
	v_mul_f32_e32 v12, v12, v12
	v_fmac_f32_e32 v12, v11, v11
	v_lshlrev_b32_e32 v11, 16, v13
	v_and_b32_e32 v13, 0xffff0000, v13
	v_mul_f32_e32 v13, v13, v13
	v_fmac_f32_e32 v13, v11, v11
	v_add_f32_e32 v11, v12, v13
	v_add_f32_e32 v14, v10, v11
	v_lshlrev_b32_e32 v10, 16, v192
	v_and_b32_e32 v11, 0xffff0000, v192
	v_lshlrev_b32_e32 v12, 16, v193
	v_and_b32_e32 v13, 0xffff0000, v193
	v_pk_add_f32 v[8:9], v[8:9], v[12:13]
	v_pk_add_f32 v[6:7], v[6:7], v[10:11]
	v_lshlrev_b32_e32 v10, 16, v194
	v_and_b32_e32 v11, 0xffff0000, v194
	v_lshlrev_b32_e32 v12, 16, v195
	v_and_b32_e32 v13, 0xffff0000, v195
	v_pk_add_f32 v[12:13], v[4:5], v[12:13]
	v_pk_add_f32 v[4:5], v[2:3], v[10:11]
	v_cvt_pk_bf16_f32 v2, v6, v7
	v_cvt_pk_bf16_f32 v3, v8, v9
	ds_bpermute_b32 v51, v117, v50
	v_cvt_pk_bf16_f32 v4, v4, v5
	v_cvt_pk_bf16_f32 v5, v12, v13
	global_store_dwordx4 v[20:21], v[2:5], off offset:256
	v_lshlrev_b32_e32 v6, 16, v2
	ds_bpermute_b32 v35, v117, v34
	v_and_b32_e32 v2, 0xffff0000, v2
	v_mul_f32_e32 v2, v2, v2
	v_fmac_f32_e32 v2, v6, v6
	v_lshlrev_b32_e32 v6, 16, v3
	v_and_b32_e32 v3, 0xffff0000, v3
	v_mul_f32_e32 v3, v3, v3
	v_fmac_f32_e32 v3, v6, v6
	v_add_f32_e32 v2, v2, v3
	v_lshlrev_b32_e32 v3, 16, v4
	v_and_b32_e32 v4, 0xffff0000, v4
	v_mul_f32_e32 v4, v4, v4
	v_fmac_f32_e32 v4, v3, v3
	v_lshlrev_b32_e32 v3, 16, v5
	v_and_b32_e32 v5, 0xffff0000, v5
	v_mul_f32_e32 v5, v5, v5
	v_fmac_f32_e32 v5, v3, v3
	v_add_f32_e32 v2, v14, v2
	v_add_f32_e32 v3, v4, v5
	v_add_f32_e32 v2, v2, v3
	ds_bpermute_b32 v19, v117, v18
	ds_bpermute_b32 v3, v117, v2
	s_waitcnt lgkmcnt(3)
	v_add_f32_e32 v50, v50, v51
	s_waitcnt lgkmcnt(2)
	v_add_f32_e32 v34, v34, v35
	ds_bpermute_b32 v51, v116, v50
	s_waitcnt lgkmcnt(2)
	v_add_f32_e32 v18, v18, v19
	s_waitcnt lgkmcnt(1)
	v_add_f32_e32 v4, v2, v3
	ds_bpermute_b32 v35, v116, v34
	ds_bpermute_b32 v19, v116, v18
	ds_bpermute_b32 v5, v116, v4
	s_and_saveexec_b64 s[6:7], vcc
	s_xor_b64 s[52:53], exec, s[6:7]
	s_cbranch_execz .LBB0_772
	v_cmp_lt_i32_e32 vcc, 2, v186
	s_and_saveexec_b64 s[6:7], vcc
	s_xor_b64 s[54:55], exec, s[6:7]
	s_andn2_saveexec_b64 s[54:55], s[54:55]
	v_mov_b32_e32 v100, v96
	v_mov_b32_e32 v101, v97
	s_or_b64 exec, exec, s[54:55]
